# P4 scan: all chunk loads issued up front (one round trip instead of four), stores younger than every load so counted waits never depend on store acks
# speedup vs baseline: 1.0092x; 1.0081x over previous
; __device__ __forceinline__ void hgrn_scan_phase(const float* __restrict__ Lst, const float* __restrict__ Dtot, float* __restrict__ Sst, int G) {
;     ...
;     for (int e = blockIdx.x * NTHR + tid; e < 8 * 16384; e += G * NTHR) {
;         const int bh = e >> 14, kv = e & 16383, kk = kv >> 7;
;         float s = 0.f;
; #pragma unroll 8
;         for (int sc = 0; sc < 32; ++sc) { const size_t u = (size_t)(bh * 32 + sc);
;             Sst[u * 16384 + kv] = s;
;             s = Dtot[u * 128 + kk] * s + Lst[u * 16384 + kv]; }
.LBB0_401:
	v_lshl_add_u64 v[4:5], s[10:11], 0, v[2:3]
	v_lshl_add_u64 v[6:7], s[10:11], 0, v[0:1]
	s_mov_b64 s[14:15], 0x1000
	s_mov_b64 s[36:37], 0x10000
	s_mov_b64 s[38:39], 0xd800000
	s_mov_b64 s[40:41], 0xb800000
	s_mov_b64 s[42:43], 0xc800000
	v_lshl_add_u64 v[8:9], v[6:7], 0, s[38:39]
	v_lshl_add_u64 v[14:15], v[4:5], 0, s[40:41]
	v_lshl_add_u64 v[16:17], v[4:5], 0, s[42:43]
	global_load_dword v40, v[8:9], off
	global_load_dword v72, v[14:15], off
	v_lshl_add_u64 v[14:15], v[14:15], 0, s[36:37]
	global_load_dword v41, v[8:9], off offset:512
	global_load_dword v73, v[14:15], off
	v_lshl_add_u64 v[14:15], v[14:15], 0, s[36:37]
	global_load_dword v42, v[8:9], off offset:1024
	global_load_dword v74, v[14:15], off
	v_lshl_add_u64 v[14:15], v[14:15], 0, s[36:37]
	global_load_dword v43, v[8:9], off offset:1536
	global_load_dword v75, v[14:15], off
	v_lshl_add_u64 v[14:15], v[14:15], 0, s[36:37]
	global_load_dword v44, v[8:9], off offset:2048
	global_load_dword v76, v[14:15], off
	v_lshl_add_u64 v[14:15], v[14:15], 0, s[36:37]
	global_load_dword v45, v[8:9], off offset:2560
	global_load_dword v77, v[14:15], off
	v_lshl_add_u64 v[14:15], v[14:15], 0, s[36:37]
	global_load_dword v46, v[8:9], off offset:3072
	global_load_dword v78, v[14:15], off
	v_lshl_add_u64 v[14:15], v[14:15], 0, s[36:37]
	global_load_dword v47, v[8:9], off offset:3584
	global_load_dword v79, v[14:15], off
	v_lshl_add_u64 v[14:15], v[14:15], 0, s[36:37]
	v_lshl_add_u64 v[8:9], v[8:9], 0, s[14:15]
	global_load_dword v48, v[8:9], off
	global_load_dword v80, v[14:15], off
	v_lshl_add_u64 v[14:15], v[14:15], 0, s[36:37]
	global_load_dword v49, v[8:9], off offset:512
	global_load_dword v81, v[14:15], off
	v_lshl_add_u64 v[14:15], v[14:15], 0, s[36:37]
	global_load_dword v50, v[8:9], off offset:1024
	global_load_dword v82, v[14:15], off
	v_lshl_add_u64 v[14:15], v[14:15], 0, s[36:37]
	global_load_dword v51, v[8:9], off offset:1536
	global_load_dword v83, v[14:15], off
	v_lshl_add_u64 v[14:15], v[14:15], 0, s[36:37]
	global_load_dword v52, v[8:9], off offset:2048
	global_load_dword v84, v[14:15], off
	v_lshl_add_u64 v[14:15], v[14:15], 0, s[36:37]
	global_load_dword v53, v[8:9], off offset:2560
	global_load_dword v85, v[14:15], off
	v_lshl_add_u64 v[14:15], v[14:15], 0, s[36:37]
	global_load_dword v54, v[8:9], off offset:3072
	global_load_dword v86, v[14:15], off
	v_lshl_add_u64 v[14:15], v[14:15], 0, s[36:37]
	global_load_dword v55, v[8:9], off offset:3584
	global_load_dword v87, v[14:15], off
	v_lshl_add_u64 v[14:15], v[14:15], 0, s[36:37]
	v_lshl_add_u64 v[8:9], v[8:9], 0, s[14:15]
	global_load_dword v56, v[8:9], off
	global_load_dword v88, v[14:15], off
	v_lshl_add_u64 v[14:15], v[14:15], 0, s[36:37]
	global_load_dword v57, v[8:9], off offset:512
	global_load_dword v89, v[14:15], off
	v_lshl_add_u64 v[14:15], v[14:15], 0, s[36:37]
	global_load_dword v58, v[8:9], off offset:1024
	global_load_dword v90, v[14:15], off
	v_lshl_add_u64 v[14:15], v[14:15], 0, s[36:37]
	global_load_dword v59, v[8:9], off offset:1536
	global_load_dword v91, v[14:15], off
	v_lshl_add_u64 v[14:15], v[14:15], 0, s[36:37]
	global_load_dword v60, v[8:9], off offset:2048
	global_load_dword v92, v[14:15], off
	v_lshl_add_u64 v[14:15], v[14:15], 0, s[36:37]
	global_load_dword v61, v[8:9], off offset:2560
	global_load_dword v93, v[14:15], off
	v_lshl_add_u64 v[14:15], v[14:15], 0, s[36:37]
	global_load_dword v62, v[8:9], off offset:3072
	global_load_dword v94, v[14:15], off
	v_lshl_add_u64 v[14:15], v[14:15], 0, s[36:37]
	global_load_dword v63, v[8:9], off offset:3584
	global_load_dword v95, v[14:15], off
	v_lshl_add_u64 v[14:15], v[14:15], 0, s[36:37]
	v_lshl_add_u64 v[8:9], v[8:9], 0, s[14:15]
	global_load_dword v64, v[8:9], off
	global_load_dword v96, v[14:15], off
	v_lshl_add_u64 v[14:15], v[14:15], 0, s[36:37]
	global_load_dword v65, v[8:9], off offset:512
	global_load_dword v97, v[14:15], off
	v_lshl_add_u64 v[14:15], v[14:15], 0, s[36:37]
	global_load_dword v66, v[8:9], off offset:1024
	global_load_dword v98, v[14:15], off
	v_lshl_add_u64 v[14:15], v[14:15], 0, s[36:37]
	global_load_dword v67, v[8:9], off offset:1536
	global_load_dword v99, v[14:15], off
	v_lshl_add_u64 v[14:15], v[14:15], 0, s[36:37]
	global_load_dword v68, v[8:9], off offset:2048
	global_load_dword v100, v[14:15], off
	v_lshl_add_u64 v[14:15], v[14:15], 0, s[36:37]
	global_load_dword v69, v[8:9], off offset:2560
	global_load_dword v101, v[14:15], off
	v_lshl_add_u64 v[14:15], v[14:15], 0, s[36:37]
	global_store_dword v[16:17], v12, off sc1
	v_lshl_add_u64 v[16:17], v[16:17], 0, s[36:37]
	s_waitcnt vmcnt(59)
	v_fmac_f32_e32 v72, v12, v40
	global_store_dword v[16:17], v72, off sc1
	v_lshl_add_u64 v[16:17], v[16:17], 0, s[36:37]
	s_waitcnt vmcnt(58)
; __device__ __forceinline__ void hgrn_scan_phase(const float* __restrict__ Lst, const float* __restrict__ Dtot, float* __restrict__ Sst, int G) {
;     ...
;     for (int e = blockIdx.x * NTHR + tid; e < 8 * 16384; e += G * NTHR) {
;         const int bh = e >> 14, kv = e & 16383, kk = kv >> 7;
;         float s = 0.f;
; #pragma unroll 8
;         for (int sc = 0; sc < 32; ++sc) { const size_t u = (size_t)(bh * 32 + sc);
;             Sst[u * 16384 + kv] = s;
;             s = Dtot[u * 128 + kk] * s + Lst[u * 16384 + kv]; }
	v_fmac_f32_e32 v73, v72, v41
	global_load_dword v70, v[8:9], off offset:3072
	global_load_dword v102, v[14:15], off
	v_lshl_add_u64 v[14:15], v[14:15], 0, s[36:37]
	global_load_dword v71, v[8:9], off offset:3584
	global_load_dword v103, v[14:15], off
	global_store_dword v[16:17], v73, off sc1
	v_lshl_add_u64 v[16:17], v[16:17], 0, s[36:37]
	s_waitcnt vmcnt(61)
	v_fmac_f32_e32 v74, v73, v42
	global_store_dword v[16:17], v74, off sc1
	v_lshl_add_u64 v[16:17], v[16:17], 0, s[36:37]
	s_waitcnt vmcnt(60)
	v_fmac_f32_e32 v75, v74, v43
	global_store_dword v[16:17], v75, off sc1
	v_lshl_add_u64 v[16:17], v[16:17], 0, s[36:37]
	s_waitcnt vmcnt(59)
	v_fmac_f32_e32 v76, v75, v44
	global_store_dword v[16:17], v76, off sc1
	v_lshl_add_u64 v[16:17], v[16:17], 0, s[36:37]
	s_waitcnt vmcnt(58)
	v_fmac_f32_e32 v77, v76, v45
	global_store_dword v[16:17], v77, off sc1
	v_lshl_add_u64 v[16:17], v[16:17], 0, s[36:37]
	s_waitcnt vmcnt(57)
	v_fmac_f32_e32 v78, v77, v46
	global_store_dword v[16:17], v78, off sc1
	v_lshl_add_u64 v[16:17], v[16:17], 0, s[36:37]
	s_waitcnt vmcnt(56)
	v_fmac_f32_e32 v79, v78, v47
	global_store_dword v[16:17], v79, off sc1
	v_lshl_add_u64 v[16:17], v[16:17], 0, s[36:37]
	s_waitcnt vmcnt(55)
	v_fmac_f32_e32 v80, v79, v48
	global_store_dword v[16:17], v80, off sc1
	v_lshl_add_u64 v[16:17], v[16:17], 0, s[36:37]
	s_waitcnt vmcnt(54)
	v_fmac_f32_e32 v81, v80, v49
	global_store_dword v[16:17], v81, off sc1
	v_lshl_add_u64 v[16:17], v[16:17], 0, s[36:37]
	s_waitcnt vmcnt(53)
	v_fmac_f32_e32 v82, v81, v50
	global_store_dword v[16:17], v82, off sc1
	v_lshl_add_u64 v[16:17], v[16:17], 0, s[36:37]
	s_waitcnt vmcnt(52)
	v_fmac_f32_e32 v83, v82, v51
	global_store_dword v[16:17], v83, off sc1
	v_lshl_add_u64 v[16:17], v[16:17], 0, s[36:37]
	s_waitcnt vmcnt(51)
	v_fmac_f32_e32 v84, v83, v52
	global_store_dword v[16:17], v84, off sc1
	v_lshl_add_u64 v[16:17], v[16:17], 0, s[36:37]
	s_waitcnt vmcnt(50)
	v_fmac_f32_e32 v85, v84, v53
	global_store_dword v[16:17], v85, off sc1
	v_lshl_add_u64 v[16:17], v[16:17], 0, s[36:37]
	s_waitcnt vmcnt(49)
	v_fmac_f32_e32 v86, v85, v54
	global_store_dword v[16:17], v86, off sc1
	v_lshl_add_u64 v[16:17], v[16:17], 0, s[36:37]
	s_waitcnt vmcnt(48)
	v_fmac_f32_e32 v87, v86, v55
	global_store_dword v[16:17], v87, off sc1
	v_lshl_add_u64 v[16:17], v[16:17], 0, s[36:37]
	s_waitcnt vmcnt(47)
	v_fmac_f32_e32 v88, v87, v56
	global_store_dword v[16:17], v88, off sc1
	v_lshl_add_u64 v[16:17], v[16:17], 0, s[36:37]
	s_waitcnt vmcnt(46)
	v_fmac_f32_e32 v89, v88, v57
	global_store_dword v[16:17], v89, off sc1
	v_lshl_add_u64 v[16:17], v[16:17], 0, s[36:37]
	s_waitcnt vmcnt(45)
	v_fmac_f32_e32 v90, v89, v58
	global_store_dword v[16:17], v90, off sc1
	v_lshl_add_u64 v[16:17], v[16:17], 0, s[36:37]
	s_waitcnt vmcnt(44)
	v_fmac_f32_e32 v91, v90, v59
	global_store_dword v[16:17], v91, off sc1
	v_lshl_add_u64 v[16:17], v[16:17], 0, s[36:37]
	s_waitcnt vmcnt(43)
	v_fmac_f32_e32 v92, v91, v60
	global_store_dword v[16:17], v92, off sc1
	v_lshl_add_u64 v[16:17], v[16:17], 0, s[36:37]
	s_waitcnt vmcnt(42)
	v_fmac_f32_e32 v93, v92, v61
	global_store_dword v[16:17], v93, off sc1
	v_lshl_add_u64 v[16:17], v[16:17], 0, s[36:37]
	s_waitcnt vmcnt(41)
	v_fmac_f32_e32 v94, v93, v62
	global_store_dword v[16:17], v94, off sc1
	v_lshl_add_u64 v[16:17], v[16:17], 0, s[36:37]
	s_waitcnt vmcnt(40)
	v_fmac_f32_e32 v95, v94, v63
	global_store_dword v[16:17], v95, off sc1
	v_lshl_add_u64 v[16:17], v[16:17], 0, s[36:37]
	s_waitcnt vmcnt(39)
	v_fmac_f32_e32 v96, v95, v64
	global_store_dword v[16:17], v96, off sc1
	v_lshl_add_u64 v[16:17], v[16:17], 0, s[36:37]
	s_waitcnt vmcnt(38)
	v_fmac_f32_e32 v97, v96, v65
	global_store_dword v[16:17], v97, off sc1
	v_lshl_add_u64 v[16:17], v[16:17], 0, s[36:37]
	s_waitcnt vmcnt(37)
	v_fmac_f32_e32 v98, v97, v66
	global_store_dword v[16:17], v98, off sc1
	v_lshl_add_u64 v[16:17], v[16:17], 0, s[36:37]
	s_waitcnt vmcnt(36)
	v_fmac_f32_e32 v99, v98, v67
	global_store_dword v[16:17], v99, off sc1
	v_lshl_add_u64 v[16:17], v[16:17], 0, s[36:37]
	s_waitcnt vmcnt(35)
	v_fmac_f32_e32 v100, v99, v68
	global_store_dword v[16:17], v100, off sc1
	v_lshl_add_u64 v[16:17], v[16:17], 0, s[36:37]
	s_waitcnt vmcnt(34)
	v_fmac_f32_e32 v101, v100, v69
	global_store_dword v[16:17], v101, off sc1
	v_lshl_add_u64 v[16:17], v[16:17], 0, s[36:37]
	s_waitcnt vmcnt(31)
	v_fmac_f32_e32 v102, v101, v70
	global_store_dword v[16:17], v102, off sc1
	s_waitcnt vmcnt(30)
	v_fmac_f32_e32 v103, v102, v71
	v_mov_b32_e32 v12, v103
	s_mov_b32 s16, 0
	s_mov_b64 s[36:37], 0x4000
	v_lshl_add_u64 v[0:1], v[0:1], 0, s[36:37]
	s_mov_b64 s[36:37], 0x200000
	v_lshl_add_u64 v[2:3], v[2:3], 0, s[36:37]
	v_add_u32_e32 v10, s5, v10
	s_mov_b32 s14, 0x1ffff
	v_cmp_lt_i32_e32 vcc, s14, v10
	s_or_b64 s[50:51], vcc, s[50:51]
	v_add_u16_e32 v11, s5, v11
	s_andn2_b64 exec, exec, s[50:51]
	s_cbranch_execnz .LBB0_400
